# as before, and the last 600 FFN2 gate/up conversion tiles moved from the retention workgroups' P7 tail to P2's idle workgroups (after the in/out-projection tiles)
# baseline (speedup 1.0000x reference)
; __device__ __forceinline__ int fresh_tid(int wv) { int l; asm volatile("v_mbcnt_lo_u32_b32 %0, -1, 0\n\tv_mbcnt_hi_u32_b32 %0, -1, %0" : "=v"(l)); return wv * 64 + l; }
; #define LAS __attribute__((address_space(3)))
; __device__ __forceinline__ void tconv_list(const float* wg, const float* wu, const float* wd, const float* win, const float* wout, unsigned char* ws, const int ntiles, LAS float* t, const int wv) {
;     const int tid = fresh_tid(wv); const int G = gridDim.x;
;     float cur[8], nxt[8];
;     int i = blockIdx.x;
;     if (i < ntiles) { const TDesc d = tconv_desc(wg, wu, wd, win, wout, ws, i);
; #pragma unroll
;         for (int e = 0; e < 8; ++e) { const int idx = e * 512 + tid, r = idx >> 6, c = idx & 63; cur[e] = __builtin_nontemporal_load(d.W + (size_t)(d.k0 + r) * d.N + d.n0 + c); } }
.Ltc3_skip:
	s_cmp_lt_u32 s2, 64
	s_cbranch_scc1 .Ltc6_skip
	v_writelane_b32 v40, s4, 4
	v_writelane_b32 v40, s5, 5
	v_writelane_b32 v40, s6, 6
	v_writelane_b32 v40, s7, 7
	v_writelane_b32 v40, s8, 8
	v_writelane_b32 v40, s9, 9
	v_writelane_b32 v40, s10, 10
	v_writelane_b32 v40, s11, 11
	v_writelane_b32 v40, s12, 12
	v_writelane_b32 v40, s13, 13
	v_writelane_b32 v40, s14, 14
	v_writelane_b32 v40, s15, 15
	v_writelane_b32 v40, s16, 16
	v_writelane_b32 v40, s17, 17
	v_writelane_b32 v40, s18, 18
	v_writelane_b32 v40, s19, 19
	v_writelane_b32 v40, s20, 20
	v_writelane_b32 v40, s21, 21
	v_writelane_b32 v40, s22, 22
	v_writelane_b32 v40, s23, 23
	v_writelane_b32 v40, s24, 24
	v_writelane_b32 v40, s25, 25
	v_writelane_b32 v40, s26, 26
	v_writelane_b32 v40, s27, 27
	v_writelane_b32 v40, s28, 28
	v_writelane_b32 v40, s29, 29
	v_writelane_b32 v40, s30, 30
	v_writelane_b32 v40, s31, 31
	s_load_dwordx2 s[24:25], s[0:1], 0xd8
	s_load_dwordx2 s[26:27], s[0:1], 0xd0
	s_load_dwordx2 s[18:19], s[0:1], 0xb8
	s_load_dwordx2 s[20:21], s[0:1], 0xc0
	s_load_dwordx2 s[22:23], s[0:1], 0xc8
	v_mbcnt_lo_u32_b32 v0, -1, 0
	v_mbcnt_hi_u32_b32 v0, -1, v0
	s_lshr_b32 s28, s33, 6
	v_lshlrev_b32_e32 v1, 2, v0
	v_lshrrev_b32_e32 v2, 5, v0
	v_and_b32_e32 v3, 31, v0
	s_mul_i32 s7, s28, 260
	v_add_u32_e32 v5, s7, v1
	v_mul_u32_u24_e32 v6, 0x208, v3
	s_lshl_b32 s7, s28, 3
	v_lshl_add_u32 v6, v2, 2, v6
	v_add_u32_e32 v6, s7, v6
	v_lshlrev_b32_e32 v3, 2, v3
	s_sub_u32 s4, s2, 64
	s_add_u32 s4, s4, 808
	s_waitcnt lgkmcnt(0)
	s_cmp_lt_u32 s4, 704
	s_cbranch_scc0 .Ltc6_seg1_0
	s_mov_b32 s7, s4
	s_and_b32 s8, s7, 15
	s_lshr_b32 s9, s7, 4
	s_mul_i32 s7, s8, 720896
	s_lshl_b32 s29, s9, 8
	s_add_u32 s7, s7, s29
	s_mul_i32 s29, s28, 11264
	s_add_u32 s7, s7, s29
	s_add_u32 s10, s18, s7
	s_addc_u32 s11, s19, 0
	s_lshr_b32 s7, s9, 1
	s_lshl_b32 s7, s7, 8
	s_and_b32 s29, s9, 1
	s_lshl_b32 s29, s29, 6
	s_add_u32 s7, s7, s29
	s_mul_i32 s7, s7, 2048
	s_lshl_b32 s29, s8, 7
	s_add_u32 s7, s7, s29
	s_mul_i32 s29, s28, 4096
	s_add_u32 s7, s7, s29
	s_add_u32 s12, s26, 0x2100000
	s_addc_u32 s13, s27, 0
	s_add_u32 s12, s12, s7
	s_addc_u32 s13, s13, 0
	s_mov_b32 s14, 90112
	s_mov_b32 s15, 32768
	s_movk_i32 s16, 2048
	s_branch .Ltc6_segend_0

; __device__ __forceinline__ void tconv_list(const float* wg, const float* wu, const float* wd, const float* win, const float* wout, unsigned char* ws, const int ntiles, LAS float* t, const int wv) {
;     ...
;     for (; i < ntiles; i += G) {
;         const TDesc d = tconv_desc(wg, wu, wd, win, wout, ws, i);
;         { const TDesc dn = tconv_desc(wg, wu, wd, win, wout, ws, i + G < ntiles ? i + G : i);
; #pragma unroll
;             for (int e = 0; e < 8; ++e) { const int idx = e * 512 + tid, r = idx >> 6, c = idx & 63; nxt[e] = __builtin_nontemporal_load(dn.W + (size_t)(dn.k0 + r) * dn.N + dn.n0 + c); } }
.Ltc6_loop:
	s_add_u32 s4, s4, 192
	s_cmp_lt_u32 s4, 1408
	s_cselect_b32 s31, 1, 0
	s_cbranch_scc0 .Ltc6_nonexta
	v_writelane_b32 v40, s8, 32
	v_writelane_b32 v40, s9, 33
	s_cmp_lt_u32 s4, 704
	s_cbranch_scc0 .Ltc6_seg1_1
	s_mov_b32 s7, s4
	s_and_b32 s8, s7, 15
	s_lshr_b32 s9, s7, 4
	s_mul_i32 s7, s8, 720896
	s_lshl_b32 s29, s9, 8
	s_add_u32 s7, s7, s29
	s_mul_i32 s29, s28, 11264
	s_add_u32 s7, s7, s29
	s_add_u32 s10, s18, s7
	s_addc_u32 s11, s19, 0
	s_lshr_b32 s7, s9, 1
	s_lshl_b32 s7, s7, 8
	s_and_b32 s29, s9, 1
	s_lshl_b32 s29, s29, 6
	s_add_u32 s7, s7, s29
	s_mul_i32 s7, s7, 2048
	s_lshl_b32 s29, s8, 7
	s_add_u32 s7, s7, s29
	s_mul_i32 s29, s28, 4096
	s_add_u32 s7, s7, s29
	s_add_u32 s12, s26, 0x2100000
	s_addc_u32 s13, s27, 0
	s_add_u32 s12, s12, s7
	s_addc_u32 s13, s13, 0
	s_mov_b32 s14, 90112
	s_mov_b32 s15, 32768
	s_movk_i32 s16, 2048
	s_branch .Ltc6_segend_1

; __device__ __forceinline__ unsigned cvt_pk_bf16(float lo, float hi) { const f32x2_t v = {lo, hi}; const bf16x2_t b = __builtin_convertvector(v, bf16x2_t); return __builtin_bit_cast(unsigned, b); }
; __device__ __forceinline__ void tconv_list(const float* wg, const float* wu, const float* wd, const float* win, const float* wout, unsigned char* ws, const int ntiles, LAS float* t, const int wv) {
;     ...
; #pragma unroll
;         for (int e = 0; e < 8; ++e) { const int idx = e * 512 + tid, r = idx >> 6, c = idx & 63; t[r * 65 + c] = cur[e]; }
;         __syncthreads();
; #pragma unroll
;         for (int e = 0; e < 4; ++e) { const int idx = e * 512 + tid, n = idx >> 5, kp = idx & 31;
;             const unsigned w = pg8::cvt_pk_bf16(t[(2 * kp) * 65 + n], t[(2 * kp + 1) * 65 + n]);
;             *(unsigned*)(d.Bt + (size_t)(d.brow0 + n) * d.K + d.k0 + 2 * kp) = w; }
;         __syncthreads();
; #pragma unroll
;         for (int e = 0; e < 8; ++e) cur[e] = nxt[e];
;     }
.Ltc6_havea:
	ds_write_b32 v5, v8 offset:0
	ds_write_b32 v5, v9 offset:2080
	ds_write_b32 v5, v10 offset:4160
	ds_write_b32 v5, v11 offset:6240
	ds_write_b32 v5, v12 offset:8320
	ds_write_b32 v5, v13 offset:10400
	ds_write_b32 v5, v14 offset:12480
	ds_write_b32 v5, v15 offset:14560
	v_mad_u32_u24 v4, v2, s30, v3
	s_waitcnt lgkmcnt(0)
	s_barrier
	ds_read2_b32 v[24:25], v6 offset0:0 offset1:65
	ds_read2_b32 v[26:27], v6 offset0:16 offset1:81
	ds_read2_b32 v[28:29], v6 offset0:32 offset1:97
	ds_read2_b32 v[30:31], v6 offset0:48 offset1:113
	s_waitcnt lgkmcnt(3)
	v_cvt_pk_bf16_f32 v32, v24, v25
	s_waitcnt lgkmcnt(2)
	v_cvt_pk_bf16_f32 v33, v26, v27
	s_waitcnt lgkmcnt(1)
	v_cvt_pk_bf16_f32 v34, v28, v29
	s_waitcnt lgkmcnt(0)
	v_cvt_pk_bf16_f32 v35, v30, v31
	global_store_dword v4, v32, s[8:9]
	s_add_u32 s8, s8, s17
	s_addc_u32 s9, s9, 0
	global_store_dword v4, v33, s[8:9]
	s_add_u32 s8, s8, s17
	s_addc_u32 s9, s9, 0
	global_store_dword v4, v34, s[8:9]
	s_add_u32 s8, s8, s17
	s_addc_u32 s9, s9, 0
	global_store_dword v4, v35, s[8:9]
	s_barrier
	s_cmp_eq_u32 s31, 0
	s_cbranch_scc1 .Ltc6_done
	s_mov_b32 s17, s15
	s_mov_b32 s30, s16
	s_mov_b64 s[8:9], s[12:13]
	s_add_u32 s4, s4, 192
	s_cmp_lt_u32 s4, 1408
	s_cselect_b32 s31, 1, 0
	s_cbranch_scc0 .Ltc6_nonextb
	v_writelane_b32 v40, s8, 32
	v_writelane_b32 v40, s9, 33
	s_cmp_lt_u32 s4, 704
	s_cbranch_scc0 .Ltc6_seg1_2
	s_mov_b32 s7, s4
	s_and_b32 s8, s7, 15
	s_lshr_b32 s9, s7, 4
	s_mul_i32 s7, s8, 720896
	s_lshl_b32 s29, s9, 8
	s_add_u32 s7, s7, s29
	s_mul_i32 s29, s28, 11264
	s_add_u32 s7, s7, s29
	s_add_u32 s10, s18, s7
	s_addc_u32 s11, s19, 0
	s_lshr_b32 s7, s9, 1
	s_lshl_b32 s7, s7, 8
	s_and_b32 s29, s9, 1
	s_lshl_b32 s29, s29, 6
	s_add_u32 s7, s7, s29
	s_mul_i32 s7, s7, 2048
	s_lshl_b32 s29, s8, 7
	s_add_u32 s7, s7, s29
	s_mul_i32 s29, s28, 4096
	s_add_u32 s7, s7, s29
	s_add_u32 s12, s26, 0x2100000
	s_addc_u32 s13, s27, 0
	s_add_u32 s12, s12, s7
	s_addc_u32 s13, s13, 0
	s_mov_b32 s14, 90112
	s_mov_b32 s15, 32768
	s_movk_i32 s16, 2048
	s_branch .Ltc6_segend_2
